# grid barriers: leaders no longer wait for the acknowledgement of the generation-flag atomics before bumping the per-XCD generation / leaving; on top of v74
# speedup vs baseline: 1.0307x; 1.0010x over previous
; __device__ __forceinline__ unsigned xb_add(unsigned* p, unsigned v) { return __hip_atomic_fetch_add(p, v, __ATOMIC_RELAXED, __HIP_MEMORY_SCOPE_AGENT); }
; __device__ __forceinline__ void phase1(const Args& a, LAS unsigned char* L) {
;     ...
;     for (int r = bid; r < 48; r += G)
;         for (int c = tid; c < DM; c += 512) { float s = bada[2048 + c];
; #pragma unroll
;             for (int q = 0; q < 4; ++q) s += modp[(size_t)(q * 48 + r) * 3072 + 2048 + c];
;             gatef[r * DM + c] = s; }
; __device__ __forceinline__ void xcd_barrier(const XcdBarrier& b) {
;     ...
;             __builtin_amdgcn_fence(__ATOMIC_ACQUIRE, "agent");
;             xb_add(&bar[XB_XGEN(b.x)], 1u);
;             asm volatile("s_waitcnt vmcnt(0)" ::: "memory");
.LBB0_98:
	s_or_b64 exec, exec, s[6:7]
	s_mov_b64 s[6:7], exec
	v_mbcnt_lo_u32_b32 v0, s6, 0
	v_mbcnt_hi_u32_b32 v0, s7, v0
	v_cmp_eq_u32_e32 vcc, 0, v0
	s_and_saveexec_b64 s[8:9], vcc
	s_cbranch_execz .LBB0_100
	s_bcnt1_i32_b64 s6, s[6:7]
	v_mov_b32_e32 v0, 0x2000
	v_mov_b32_e32 v1, s6
	global_atomic_add v0, v1, s[4:5] offset:1024
.LBB0_100:
	s_or_b64 exec, exec, s[8:9]
.LBB0_101:
	s_or_b64 exec, exec, s[0:1]
	s_add_u32 s22, s28, 0x1e400000
	s_waitcnt lgkmcnt(0)
	v_mov_b32_e32 v0, v180
	s_addc_u32 s23, s29, 0
	s_barrier
	s_cmp_lt_i32 s2, 0xf8
	v_readfirstlane_b32 s12, v0
	s_cbranch_scc1 .LBB0_107
	s_mov_b32 s98, s2
	s_mov_b32 s99, s30
	s_sub_i32 s2, s2, 0xf8
	s_mov_b32 s30, 8
	v_ashrrev_i32_e32 v1, 31, v0
	s_movk_i32 s0, 0x400
	v_lshlrev_b64 v[8:9], 2, v[0:1]
	v_cmp_gt_i32_e32 vcc, s0, v0
	v_lshl_add_u64 v[4:5], s[54:55], 0, v[8:9]
	s_mov_b64 s[0:1], 0x2000
	s_lshl_b32 s13, s30, 10
	v_lshl_add_u64 v[4:5], v[4:5], 0, s[0:1]
	s_mul_i32 s0, s2, 0x3000
	s_mul_hi_i32 s1, s2, 0x3000
	s_add_u32 s0, s28, s0
	s_addc_u32 s1, s29, s1
	v_lshl_add_u64 v[6:7], s[0:1], 0, v[8:9]
	s_mov_b64 s[0:1], 0x1e102000
	v_lshl_add_u64 v[8:9], s[28:29], 0, v[8:9]
	v_add_u32_e32 v18, 0xfffffe00, v0
	v_lshl_add_u32 v2, s2, 10, v0
	v_lshl_add_u64 v[6:7], v[6:7], 0, s[0:1]
	s_mul_hi_i32 s5, s30, 0x3000
	s_mul_i32 s4, s30, 0x3000
	v_lshl_add_u64 v[8:9], v[8:9], 0, s[0:1]
	s_add_i32 s14, s2, 48
	s_add_i32 s15, s2, 0x60
	s_add_i32 s16, s2, 0x90
	s_movk_i32 s17, 0x1ff
	v_mov_b32_e32 v1, 0x3000
	s_mov_b32 s33, s2
	s_branch .LBB0_104

;     __device__ bool next(int i, Unit& u) const { if (i >= 2) return false; const int x = c & 7, j = c >> 3; u.pm = 64 * i + 8 * x + (j >> 2); u.pn = j & 3; u.ao = 0; u.bo = 0; u.ks = 0; return true; }
;     __device__ bool next(int i, Unit& u) const { if (i >= 1 || c >= 64) return false; u.pm = 128 + (c & 3); u.pn = (c >> 2) & 3; u.ks = c >> 4; u.ao = u.ks * 512; u.bo = u.ks * 512; return true; }
; __device__ __forceinline__ unsigned xb_ld(unsigned* p)              { return __hip_atomic_load(p, __ATOMIC_RELAXED, __HIP_MEMORY_SCOPE_AGENT); }
; #define XB_SPIN(cond, bar) do { unsigned _sp = 0; while (cond) { __builtin_amdgcn_s_sleep(1); \
;     if ((++_sp & 255u) == 0u) { if (xb_ld(&(bar)[XB_TMO])) break; if (_sp > XB_SPIN_CAP) { atomicAdd(&(bar)[XB_TMO], 1u); break; } } } } while (0)
;     __device__ bool next(int i, Unit& u) const {
;         const long L = (long)i * G + c; if (L >= nwg) return false;
;         int wgid = (int)L; { const int q = nwg / NXCD, r = nwg % NXCD, xcd = wgid % NXCD, off = wgid / NXCD; wgid = (xcd < r ? xcd * (q + 1) : r * (q + 1) + (xcd - r) * q) + off; }
;         const int nig = WGM * nN, gid = wgid / nig, fm = gid * WGM, gsz = (nM - fm) < WGM ? (nM - fm) : WGM;
;         u.pm = fm + ((wgid % nig) % gsz); u.pn = (wgid % nig) / gsz; u.ao = u.pn * acol; u.bo = 0; u.ks = 0; return true;
; __device__ __forceinline__ void xcd_barrier(const XcdBarrier& b) {
;     ...
;             asm volatile("s_waitcnt vmcnt(0)" ::: "memory");
;         } else {
;             XB_SPIN(xb_ld(&bar[XB_XGEN(b.x)]) == gen, bar);
;             __builtin_amdgcn_fence(__ATOMIC_ACQUIRE, "agent");
;             asm volatile("s_waitcnt vmcnt(0)" ::: "memory");
;         }
;     }
;     __syncthreads();
.LBB0_174:
	s_or_b64 exec, exec, s[8:9]
.LBB0_175:
	s_or_b64 exec, exec, s[0:1]
	s_waitcnt vmcnt(1)
	v_mov_b32_e32 v8, v180
	s_cmpk_lt_i32 s2, 0xe70
	s_waitcnt lgkmcnt(0)
	s_barrier
	s_cselect_b64 s[0:1], -1, 0
	s_cmpk_gt_i32 s2, 0xe6f
	v_readfirstlane_b32 s12, v8
	s_cbranch_scc1 .LBB0_177
	s_and_b32 s4, s2, 7
	s_lshr_b32 s5, s2, 3
	s_cmpk_lt_u32 s5, 0x18c
	s_cbranch_scc0 .Lxpl1_xp
	s_mul_i32 s4, s4, 0x18c
	s_add_i32 s4, s4, s5
	s_lshr_b32 s6, s4, 6
	s_mul_i32 s6, s6, 0xaaab
	s_lshr_b32 s6, s6, 17
	s_mul_i32 s7, s6, 0xc0
	s_sub_i32 s8, s4, s7
	s_mov_b32 s10, 4
	s_branch .Lxpl1_common

; #define OPAQUE_TID() int tid = threadIdx.x; asm volatile("" : "+v"(tid)); const int lane = tid & 63, wave = __builtin_amdgcn_readfirstlane(tid >> 6); (void)lane; (void)wave
; __device__ __forceinline__ unsigned xb_ld(unsigned* p)              { return __hip_atomic_load(p, __ATOMIC_RELAXED, __HIP_MEMORY_SCOPE_AGENT); }
; #define XB_SPIN(cond, bar) do { unsigned _sp = 0; while (cond) { __builtin_amdgcn_s_sleep(1); \
;     if ((++_sp & 255u) == 0u) { if (xb_ld(&(bar)[XB_TMO])) break; if (_sp > XB_SPIN_CAP) { atomicAdd(&(bar)[XB_TMO], 1u); break; } } } } while (0)
; __device__ __forceinline__ void pool_prepass(const Args& a) {
;     OPAQUE_TID();
;     const bf16_t* U = (const bf16_t*)(a.ws + WS_U);
;     bf16_t* PB = (bf16_t*)a.out;
;     const int G = gridDim.x, gq = wave & 3, ch = gq * 256 + (lane & 31) * 8;
;     for (int it = blockIdx.x; it < MT / 64; it += G) {
;         const int row0 = (it * 4 + (wave >> 2) * 2 + (lane >> 5)) * 16;
;         if (gq == 0) pool_run<2>(a, U, PB, row0, ch);
;         else if (gq == 1) pool_run<4>(a, U, PB, row0, ch);
;         else if (gq == 2) pool_run<8>(a, U, PB, row0, ch);
;         else pool_run<16>(a, U, PB, row0, ch);
; __device__ __forceinline__ void xcd_barrier(const XcdBarrier& b) {
;     ...
;             asm volatile("s_waitcnt vmcnt(0)" ::: "memory");
;         } else {
;             XB_SPIN(xb_ld(&bar[XB_XGEN(b.x)]) == gen, bar);
;             __builtin_amdgcn_fence(__ATOMIC_ACQUIRE, "agent");
;             asm volatile("s_waitcnt vmcnt(0)" ::: "memory");
;         }
;     }
;     __syncthreads();
.LBB0_340:
	s_or_b64 exec, exec, s[8:9]
.LBB0_341:
	s_or_b64 exec, exec, s[0:1]
	s_bitcmp0_b32 s2, 5
	s_cselect_b64 s[40:41], -1, 0
	s_and_b64 vcc, exec, s[40:41]
	s_waitcnt lgkmcnt(0)
	s_barrier
	s_cbranch_vccnz .LBB0_642
	s_and_b32 s98, s2, 31
	s_lshr_b32 s99, s2, 6
	s_lshl_b32 s99, s99, 5
	s_or_b32 s98, s98, s99
	s_movk_i32 s99, 0x80
	v_mov_b32_e32 v0, v180
	s_cmpk_gt_i32 s98, 0x20f
	v_readfirstlane_b32 s0, v0
	s_cbranch_scc1 .LBB0_642
	v_lshlrev_b32_e32 v1, 3, v0
	s_bfe_u32 s12, s0, 0x20006
	v_and_b32_e32 v1, 0xf8, v1
	s_ashr_i32 s0, s0, 7
	v_lshl_or_b32 v124, s12, 8, v1
	s_and_b32 s0, s0, -2
	s_lshl_b32 s1, s98, 2
	v_bfe_u32 v125, v0, 5, 1
	v_mov_b32_e32 v127, 0
	v_lshlrev_b32_e32 v126, 1, v124
	s_add_i32 s13, s1, s0
	v_lshl_add_u64 v[128:129], s[28:29], 0, v[126:127]
	v_lshl_add_u64 v[130:131], s[26:27], 0, v[126:127]
	v_lshlrev_b32_e32 v126, 2, v124
	v_or_b32_e32 v0, s13, v125
	v_lshl_add_u64 v[132:133], s[44:45], 0, v[126:127]
	s_lshl_b32 s14, s99, 2
	v_lshl_or_b32 v134, v0, 4, 15
	s_lshl_b32 s15, s99, 6
	s_movk_i32 s42, 0x7ff
	v_mov_b32_e32 v139, 0xfffff80f
	v_not_b32_e32 v170, 16
	v_mov_b32_e32 v171, 0x7ff
	s_movk_i32 s43, 0x3800
	s_mov_b32 s52, 0x3d800000
	s_mov_b32 s53, 0x3e000000
	s_mov_b32 s54, 0x3e800000
	v_mov_b32_e32 v172, 0x7f1
	v_mov_b32_e32 v173, 0x2100000
	v_mov_b32_e32 v174, 0x2540040
	v_mov_b32_e32 v175, 0x41800000
	v_mov_b32_e32 v176, 0x41000000
	s_mov_b32 s55, s98
	s_branch .LBB0_345

; #define OPAQUE_TID() int tid = threadIdx.x; asm volatile("" : "+v"(tid)); const int lane = tid & 63, wave = __builtin_amdgcn_readfirstlane(tid >> 6); (void)lane; (void)wave
; #define YM_LOAD(row) do { const bf16_t* ur_ = U + (size_t)(row) * LDU + cbase; _Pragma("unroll") for (int hp = 0; hp < 2; ++hp) { \
;         nh[hp] = *(const u32x4*)(ur_ + C_V + 512 * hp); nz[hp] = *(const u32x4*)(ur_ + C_ZM + 512 * hp); } } while (0)
; __device__ __forceinline__ unsigned xb_ld(unsigned* p)              { return __hip_atomic_load(p, __ATOMIC_RELAXED, __HIP_MEMORY_SCOPE_AGENT); }
; #define XB_SPIN(cond, bar) do { unsigned _sp = 0; while (cond) { __builtin_amdgcn_s_sleep(1); \
;     if ((++_sp & 255u) == 0u) { if (xb_ld(&(bar)[XB_TMO])) break; if (_sp > XB_SPIN_CAP) { atomicAdd(&(bar)[XB_TMO], 1u); break; } } } } while (0)
; __device__ __forceinline__ void ym_finalize(const Args& a, bool dry = false) {
;     OPAQUE_TID();
;     bf16_t* U = (bf16_t*)(a.ws + WS_U);
;     const int gw = blockIdx.x * 8 + wave, NGW = gridDim.x * 8;
;     const int cbase = (lane >> 5) * 256 + 8 * (lane & 31);
;     f32x4 gh[2][2];
; #pragma unroll
;     for (int hp = 0; hp < 2; ++hp) { gh[hp][0] = *(const f32x4*)(a.in[16] + cbase + 512 * hp); gh[hp][1] = *(const f32x4*)(a.in[16] + cbase + 512 * hp + 4); }
;     u32x4 nh[2], nz[2];
;     ...
;     if (gw < MT) YM_LOAD(gw);
;     for (int row = gw; row < MT; row += NGW) {
;         u32x4 ch[2], cz[2];
; #pragma unroll
;         for (int hp = 0; hp < 2; ++hp) { ch[hp] = nh[hp]; cz[hp] = nz[hp]; }
;         if (row + NGW < MT) YM_LOAD(row + NGW);
; __device__ __forceinline__ void xcd_barrier(const XcdBarrier& b) {
;     ...
;             asm volatile("s_waitcnt vmcnt(0)" ::: "memory");
;         } else {
;             XB_SPIN(xb_ld(&bar[XB_XGEN(b.x)]) == gen, bar);
;             __builtin_amdgcn_fence(__ATOMIC_ACQUIRE, "agent");
;             asm volatile("s_waitcnt vmcnt(0)" ::: "memory");
;         }
;     }
;     __syncthreads();
.LBB0_1127:
	s_or_b64 exec, exec, s[8:9]
.LBB0_1128:
	s_or_b64 exec, exec, s[0:1]
	s_bitcmp0_b32 s2, 3
	s_cselect_b64 s[4:5], -1, 0
	s_and_b64 vcc, exec, s[4:5]
	s_waitcnt lgkmcnt(0)
	s_barrier
	s_cbranch_vccnz .LBB0_1134
	v_mov_b32_e32 v20, v180
	v_readlane_b32 s1, v254, 3
	v_readfirstlane_b32 s0, v20
	s_ashr_i32 s0, s0, 6
	s_add_i32 s10, s0, s1
	s_cmp_gt_i32 s10, 0x83ff
	s_cbranch_scc1 .LBB0_1134
	v_lshlrev_b32_e32 v0, 3, v20
	s_mul_i32 s0, s10, 0x3800
	v_and_b32_e32 v8, 0x1f8, v0
	s_mul_hi_i32 s1, s10, 0x3800
	s_add_u32 s0, s28, s0
	s_addc_u32 s1, s29, s1
	v_lshlrev_b32_e32 v48, 1, v8
	v_mov_b32_e32 v49, 0
	v_lshlrev_b32_e32 v21, 2, v8
	v_lshl_add_u64 v[8:9], s[0:1], 0, v[48:49]
	s_movk_i32 s6, 0x3000
	v_add_co_u32_e32 v22, vcc, s6, v8
	s_movk_i32 s11, 0x1000
	s_nop 0
	v_addc_co_u32_e32 v23, vcc, 0, v9, vcc
	v_add_co_u32_e32 v24, vcc, s11, v8
	global_load_dwordx4 v[0:3], v21, s[20:21] offset:2048
	global_load_dwordx4 v[4:7], v21, s[20:21] offset:2064
	v_addc_co_u32_e32 v25, vcc, 0, v9, vcc
	global_load_dwordx4 v[36:39], v[24:25], off
	global_load_dwordx4 v[16:19], v[24:25], off offset:1024
	global_load_dwordx4 v[44:47], v[22:23], off
	global_load_dwordx4 v[40:43], v[22:23], off offset:1024
	global_load_dwordx4 v[8:11], v21, s[20:21]
	global_load_dwordx4 v[12:15], v21, s[20:21] offset:16
	v_mbcnt_hi_u32_b32 v21, -1, v181
	v_and_b32_e32 v22, 64, v21
	v_xor_b32_e32 v23, 1, v21
	v_add_u32_e32 v22, 64, v22
	v_xor_b32_e32 v24, 2, v21
	v_cmp_lt_i32_e32 vcc, v23, v22
	v_xor_b32_e32 v25, 4, v21
	v_xor_b32_e32 v26, 8, v21
	v_cndmask_b32_e32 v23, v21, v23, vcc
	v_cmp_lt_i32_e32 vcc, v24, v22
	v_xor_b32_e32 v27, 16, v21
	s_add_i32 s6, s10, s34
	v_cndmask_b32_e32 v24, v21, v24, vcc
	v_cmp_lt_i32_e32 vcc, v25, v22
	v_and_b32_e32 v20, 63, v20
	s_mul_hi_i32 s7, s6, 0x3800
	v_cndmask_b32_e32 v25, v21, v25, vcc
	v_cmp_lt_i32_e32 vcc, v26, v22
	s_mulk_i32 s6, 0x3800
	v_lshlrev_b32_e32 v48, 4, v20
	v_cndmask_b32_e32 v26, v21, v26, vcc
	v_cmp_lt_i32_e32 vcc, v27, v22
	v_lshlrev_b32_e32 v51, 2, v23
	v_lshlrev_b32_e32 v52, 2, v24
	v_cndmask_b32_e32 v21, v21, v27, vcc
	v_lshlrev_b32_e32 v53, 2, v25
	v_lshlrev_b32_e32 v54, 2, v26
	v_lshlrev_b32_e32 v55, 2, v21
	s_add_u32 s6, s28, s6
	s_mul_hi_i32 s12, s34, 0x3800
	s_mul_i32 s13, s34, 0x3800
	v_mov_b32_e32 v50, 0x358637bd
	s_mov_b32 s14, 0x800000
	s_addc_u32 s7, s29, s7
	s_waitcnt vmcnt(5)
	v_mov_b64_e32 v[28:29], v[36:37]
	s_waitcnt vmcnt(4)
	v_mov_b64_e32 v[26:27], v[18:19]
	s_waitcnt vmcnt(3)
	v_mov_b64_e32 v[20:21], v[44:45]
	s_waitcnt vmcnt(2)
	v_mov_b64_e32 v[32:33], v[40:41]
	v_mov_b64_e32 v[24:25], v[16:17]
	v_mov_b64_e32 v[30:31], v[38:39]
	v_mov_b64_e32 v[22:23], v[46:47]
	v_mov_b64_e32 v[34:35], v[42:43]
	s_branch .LBB0_1132

; #define PG8_WAIT_V(n) asm volatile("s_waitcnt vmcnt(" #n ")" ::: "memory")
; template <class Epi, class Sched, bool ALIGN_EPI, bool SP2>
; __device__ __forceinline__ void gemm_phase(LAS unsigned char* lds, const Gemm g, const Sched& S, const Epi& E) {
;     int tid = threadIdx.x; asm volatile("" : "+v"(tid));
;     const int wid = __builtin_amdgcn_readfirstlane(tid >> 6), lane = tid & 63, wr = wid >> 2, wc = wid & 3, fr = lane & 15, fq = lane >> 4;
;     const int K = g.K, nt = K / BK, lda = g.lda;
;     unsigned voffA[2], voffB[2];
; #pragma unroll
;     for (int i = 0; i < 2; ++i) { int R, C; stage_rc(tid * 16 + i * 8192, R, C); const int Rb = (R & ~31) + perm32(R & 31);
;         voffA[i] = (unsigned)(R * lda + C) * 2u; voffB[i] = (unsigned)(Rb * g.ldb + C) * 2u; }
;     const size_t kstep = (size_t)(BK * 2);
;     const size_t hstepA = (size_t)HALF * lda * 2, hstepB = (size_t)HALF * g.ldb * 2;
;     const size_t tstepA = 2 * hstepA, tstepB = 2 * hstepB;
;     const unsigned ldsw = (unsigned)wid * 1024u;
;     const int aoff = lds_byte(wr * 64 + fr, fq * 8), boff = lds_byte(wc * 32 + fr, fq * 8);
;     ...
;     Unit cur, nxt; int ui = 0;
;     if (!S.next(0, cur)) return;
;     f32x4 acc[2][2][4][2];
; #pragma unroll
;     for (int a = 0; a < 2; ++a)
; #pragma unroll
;         for (int b = 0; b < 2; ++b)
; #pragma unroll
;             for (int m = 0; m < 4; ++m)
; #pragma unroll
;                 for (int n = 0; n < 2; ++n) acc[a][b][m][n] = (f32x4){0.f, 0.f, 0.f, 0.f};
;     bf16x8 At[4][2], B0[2][2], B1[2][2];
;     const char* cA = (const char*)g.A + (size_t)cur.pm * tstepA + (size_t)cur.ao * 2; const char* cB = (const char*)g.Bt + (size_t)cur.pn * tstepB + (size_t)cur.bo * 2;
;     if constexpr (SP2) {
;         PG8_STAGE(PG8_SB(0, 0), cB, voffB); PG8_STAGE(PG8_SB(0, 1), cB + hstepB, voffB); PG8_STAGE(PG8_SA(0, 0), cA, voffA); PG8_STAGE(PG8_SA(0, 1), cA + hstepA, voffA);
;         if (wr == 1) PG8_BAR;
;         PG8_WAIT_V(2); PG8_BAR;
; __device__ __forceinline__ void xcd_barrier(const XcdBarrier& b) {
;     ...
;             asm volatile("s_waitcnt vmcnt(0)" ::: "memory");
;         } else {
;             XB_SPIN(xb_ld(&bar[XB_XGEN(b.x)]) == gen, bar);
;             __builtin_amdgcn_fence(__ATOMIC_ACQUIRE, "agent");
;             asm volatile("s_waitcnt vmcnt(0)" ::: "memory");
;         }
;     }
;     __syncthreads();
.LBB0_1205:
	s_or_b64 exec, exec, s[8:9]
.LBB0_1206:
	s_or_b64 exec, exec, s[0:1]
	v_mov_b32_e32 v9, v180
	s_waitcnt lgkmcnt(0)
	s_barrier
	s_mov_b32 s4, 0xfffe0
	v_ashrrev_i32_e32 v1, 31, v9
	v_lshrrev_b32_e32 v1, 26, v1
	v_add_u32_e32 v1, v9, v1
	v_ashrrev_i32_e32 v8, 6, v1
	v_bfe_i32 v1, v9, 27, 1
	v_lshlrev_b32_e32 v0, 4, v9
	v_lshrrev_b32_e32 v1, 22, v1
	v_add_u32_e32 v1, v0, v1
	v_and_b32_e32 v1, 0xfffffc00, v1
	v_sub_u32_e32 v1, v0, v1
	v_lshrrev_b32_e32 v2, 4, v1
	v_bitop3_b32 v1, v2, v1, 32 bitop3:0x6c
	v_ashrrev_i32_e32 v3, 31, v1
	v_lshrrev_b32_e32 v3, 26, v3
	v_add_u32_e32 v3, v1, v3
	v_lshlrev_b32_e32 v2, 3, v8
	v_ashrrev_i32_e32 v10, 6, v3
	v_and_b32_e32 v3, 0xc0, v3
	v_and_b32_e32 v2, -16, v2
	v_sub_u32_e32 v1, v1, v3
	v_mov_b32_e32 v3, 1
	v_add_u32_e32 v2, v10, v2
	v_lshlrev_b32_e32 v4, 5, v8
	v_ashrrev_i16_sdwa v1, v3, sext(v1) dst_sel:DWORD dst_unused:UNUSED_PAD src0_sel:DWORD src1_sel:BYTE_0
	v_and_b32_e32 v11, 32, v4
	v_bfe_i32 v12, v1, 0, 16
	v_lshlrev_b32_e32 v4, 1, v2
	v_lshrrev_b32_e32 v5, 2, v2
	v_and_b32_e32 v6, 3, v10
	s_movk_i32 s1, 0x1c00
	v_add_u32_e32 v1, v11, v12
	v_and_b32_e32 v4, 24, v4
	v_and_b32_e32 v5, 4, v5
	v_and_or_b32 v6, v2, s4, v6
	v_mul_lo_u32 v2, v2, s1
	v_or3_b32 v4, v6, v5, v4
	v_add_lshl_u32 v144, v1, v2, 1
	v_lshlrev_b32_e32 v1, 1, v1
	v_add_u32_e32 v0, 0x2000, v0
	v_lshl_add_u32 v146, v4, 12, v1
	v_ashrrev_i32_e32 v1, 31, v0
	v_lshrrev_b32_e32 v1, 22, v1
	v_add_u32_e32 v1, v0, v1
	v_ashrrev_i32_e32 v13, 10, v1
	v_mul_i32_i24_e32 v1, 0x400, v13
	v_sub_u32_e32 v0, v0, v1
	v_lshrrev_b32_e32 v1, 4, v0
	v_bitop3_b32 v0, v1, v0, 32 bitop3:0x6c
	v_ashrrev_i32_e32 v2, 31, v0
	v_lshrrev_b32_e32 v2, 26, v2
	v_lshlrev_b32_e32 v1, 3, v13
	v_add_u32_e32 v2, v0, v2
	v_and_b32_e32 v1, -16, v1
	v_ashrrev_i32_e32 v14, 6, v2
	v_lshlrev_b32_e32 v4, 5, v13
	v_add_u32_e32 v1, v14, v1
	v_and_b32_e32 v15, 32, v4
	v_and_b32_e32 v4, 3, v14
	s_add_u32 s50, s28, 0x1dc00000
	v_readfirstlane_b32 s0, v9
	v_and_or_b32 v4, v1, s4, v4
	v_readlane_b32 s4, v254, 3
	s_addc_u32 s51, s29, 0
	s_ashr_i32 s5, s0, 6
	v_and_b32_e32 v2, 0xc0, v2
	s_and_b32 s53, s4, 56
	s_ashr_i32 s4, s2, 5
	s_bfe_u32 s55, s2, 0x20003
	v_sub_u32_e32 v0, v0, v2
	s_ashr_i32 s16, s0, 8
	s_add_i32 s53, s53, s4
	s_lshl_b32 s54, s5, 10
	s_lshl_b32 s4, s55, 20
	v_ashrrev_i16_sdwa v0, v3, sext(v0) dst_sel:DWORD dst_unused:UNUSED_PAD src0_sel:DWORD src1_sel:BYTE_0
	s_add_u32 s6, s50, s4
	v_bfe_i32 v16, v0, 0, 16
	v_lshlrev_b32_e32 v2, 1, v1
	v_lshrrev_b32_e32 v3, 2, v1
	s_addc_u32 s7, s51, 0
	s_add_i32 s56, s54, 0
	v_add_u32_e32 v0, v15, v16
	v_and_b32_e32 v2, 24, v2
	v_and_b32_e32 v3, 4, v3
	v_mul_lo_u32 v1, v1, s1
	s_add_i32 m0, s56, 0x10000
	v_or3_b32 v2, v4, v3, v2
	v_add_lshl_u32 v148, v0, v1, 1
	v_lshlrev_b32_e32 v0, 1, v0
	global_load_lds_dwordx4 v146, s[6:7]
	s_add_i32 m0, s56, 0x12000
	v_lshl_add_u32 v150, v2, 12, v0
	s_add_u32 s8, s6, 0x80000
	global_load_lds_dwordx4 v150, s[6:7]
	s_addc_u32 s9, s7, 0
	s_add_i32 m0, s56, 0x14000
	s_mul_i32 s11, s53, 0x380000
	global_load_lds_dwordx4 v146, s[8:9]
	s_add_i32 m0, s56, 0x16000
	s_mul_hi_i32 s10, s53, 0x380000
	v_mov_b32_e32 v153, 0
	global_load_lds_dwordx4 v150, s[8:9]
	s_add_u32 s8, s28, s11
	s_addc_u32 s9, s29, s10
	v_mov_b32_e32 v145, v153
	s_mov_b64 s[10:11], 0x800
	s_add_u32 s42, s8, 0x800
	v_lshl_add_u64 v[0:1], s[8:9], 0, v[144:145]
	s_addc_u32 s43, s9, 0
	v_lshl_add_u64 v[2:3], v[0:1], 0, s[10:11]
	s_mov_b32 m0, s56
	v_mov_b32_e32 v149, v153
	s_add_i32 s57, s56, 0x2000
	global_load_lds_dwordx4 v[2:3], off
	v_lshl_add_u64 v[2:3], s[8:9], 0, v[148:149]
	s_add_u32 s8, s8, 0x1c0800
	v_lshl_add_u64 v[4:5], v[2:3], 0, s[10:11]
	s_mov_b32 m0, s57
	s_addc_u32 s9, s9, 0
	s_add_i32 s58, s56, 0x4000
	global_load_lds_dwordx4 v[4:5], off
	s_mov_b32 m0, s58
	s_add_i32 s59, s56, 0x6000
	global_load_lds_dwordx4 v144, s[8:9]
	s_mov_b32 m0, s59
	v_mov_b32_e32 v147, v153
	global_load_lds_dwordx4 v148, s[8:9]
	v_mov_b32_e32 v151, v153
	s_cmp_eq_u32 s16, 1
	v_lshl_add_u64 v[4:5], s[6:7], 0, v[146:147]
	s_cselect_b64 s[8:9], -1, 0
	s_cmp_lg_u32 s16, 1
	v_lshl_add_u64 v[6:7], s[6:7], 0, v[150:151]
	s_cbranch_scc1 .LBB0_1208
	s_barrier

; #define OPAQUE_TID() int tid = threadIdx.x; asm volatile("" : "+v"(tid)); const int lane = tid & 63, wave = __builtin_amdgcn_readfirstlane(tid >> 6); (void)lane; (void)wave
; __device__ __forceinline__ unsigned xb_ld(unsigned* p)              { return __hip_atomic_load(p, __ATOMIC_RELAXED, __HIP_MEMORY_SCOPE_AGENT); }
; __device__ __forceinline__ unsigned xb_add(unsigned* p, unsigned v) { return __hip_atomic_fetch_add(p, v, __ATOMIC_RELAXED, __HIP_MEMORY_SCOPE_AGENT); }
; #define XB_SPIN(cond, bar) do { unsigned _sp = 0; while (cond) { __builtin_amdgcn_s_sleep(1); \
;     if ((++_sp & 255u) == 0u) { if (xb_ld(&(bar)[XB_TMO])) break; if (_sp > XB_SPIN_CAP) { atomicAdd(&(bar)[XB_TMO], 1u); break; } } } } while (0)
; __device__ __forceinline__ void sample_finalize(const Args& a) {
;     OPAQUE_TID();
;     const int gw = blockIdx.x * 8 + wave, NGW = gridDim.x * 8;
;     const float* part = (const float*)(a.ws + WS_PART); const float* gatef = (const float*)(a.ws + WS_GATEF);
;     for (int r = gw; r < MS; r += NGW) {
;         f32x4 v[4]; float ss = 0.f;
; #pragma unroll
;         for (int j = 0; j < 4; ++j) { const int col = 4 * lane + 256 * j;
;             f32x4 p = *(const f32x4*)(part + (size_t)r * DM + col);
; #pragma unroll
;             for (int ks = 1; ks < 4; ++ks) p += *(const f32x4*)(part + ((size_t)ks * MS + r) * DM + col);
;             v[j] = *(const f32x4*)(a.in[1] + (size_t)r * DM + col) + *(const f32x4*)(gatef + (16 + (r >> 5)) * DM + col) * p;
;             ss += (v[j][0] * v[j][0] + v[j][1] * v[j][1]) + (v[j][2] * v[j][2] + v[j][3] * v[j][3]); }
;         const float rr = rsqrtf(wave_sum(ss) * (1.f / DM) + EPS);
; __device__ __forceinline__ void xcd_barrier(const XcdBarrier& b) {
;     ...
;             __builtin_amdgcn_fence(__ATOMIC_ACQUIRE, "agent");
;             xb_add(&bar[XB_XGEN(b.x)], 1u);
;             asm volatile("s_waitcnt vmcnt(0)" ::: "memory");
;         } else {
;             XB_SPIN(xb_ld(&bar[XB_XGEN(b.x)]) == gen, bar);
;             __builtin_amdgcn_fence(__ATOMIC_ACQUIRE, "agent");
;             asm volatile("s_waitcnt vmcnt(0)" ::: "memory");
;         }
;     }
;     __syncthreads();
.LBB0_1309:
	s_or_b64 exec, exec, s[6:7]
	s_mov_b64 s[6:7], exec
	v_mbcnt_lo_u32_b32 v0, s6, 0
	v_mbcnt_hi_u32_b32 v0, s7, v0
	v_cmp_eq_u32_e32 vcc, 0, v0
	s_and_saveexec_b64 s[8:9], vcc
	s_cbranch_execz .LBB0_1311
	s_bcnt1_i32_b64 s3, s[6:7]
	v_mov_b32_e32 v0, 0x2000
	v_mov_b32_e32 v1, s3
	global_atomic_add v0, v1, s[4:5] offset:1024
.LBB0_1311:
	s_or_b64 exec, exec, s[8:9]
.LBB0_1312:
	s_or_b64 exec, exec, s[0:1]
	s_waitcnt lgkmcnt(0)
	s_barrier
	s_nop 0
	v_readfirstlane_b32 s0, v180
	s_ashr_i32 s1, s0, 6
	v_readlane_b32 s0, v254, 3
	s_add_i32 s0, s1, s0
	s_cmpk_gt_i32 s0, 0x3ff
	s_cbranch_scc1 .LBB0_1315
	v_xor_b32_e32 v0, 1, v176
	v_cmp_lt_i32_e32 vcc, v0, v179
	s_lshl_b32 s2, s2, 8
	s_lshl_b32 s1, s1, 5
	v_cndmask_b32_e32 v0, v176, v0, vcc
	v_lshlrev_b32_e32 v8, 2, v0
	v_xor_b32_e32 v0, 2, v176
	v_cmp_lt_i32_e32 vcc, v0, v179
	s_add_i32 s10, s2, s1
	s_ashr_i32 s1, s0, 31
	v_cndmask_b32_e32 v0, v176, v0, vcc
	v_lshlrev_b32_e32 v9, 2, v0
	v_xor_b32_e32 v0, 4, v176
	v_cmp_lt_i32_e32 vcc, v0, v179
	s_lshl_b32 s11, s30, 8
	s_lshl_b64 s[6:7], s[0:1], 12
	v_cndmask_b32_e32 v0, v176, v0, vcc
	v_lshlrev_b32_e32 v10, 2, v0
	v_xor_b32_e32 v0, 8, v176
	v_cmp_lt_i32_e32 vcc, v0, v179
	s_add_u32 s2, s28, s6
	s_addc_u32 s3, s29, s7
	v_cndmask_b32_e32 v0, v176, v0, vcc
	v_lshlrev_b32_e32 v11, 2, v0
	v_lshlrev_b32_e32 v0, 4, v180
	s_ashr_i32 s35, s34, 31
	v_and_b32_e32 v0, 0x3f0, v0
	v_mov_b32_e32 v1, 0
	s_lshl_b64 s[4:5], s[34:35], 12
	v_lshl_add_u64 v[2:3], s[24:25], 0, v[0:1]
	v_lshl_add_u64 v[4:5], s[22:23], 0, v[0:1]
	v_lshl_add_u64 v[6:7], s[26:27], 0, v[0:1]
	v_and_b32_e32 v0, 63, v180
	s_add_u32 s6, s38, s6
	v_lshlrev_b32_e32 v0, 4, v0
	s_addc_u32 s7, s39, s7
	v_mov_b32_e32 v12, 0x358637bd
	s_mov_b32 s1, 0x800000
